# adds hand-written neighbourhood-attention (biased) tile body: bias loads batched, window mask by compare+select
# speedup vs baseline: 1.0603x; 1.0132x over previous
.LBB0_383:
	s_and_b32 s2, s27, 3
	v_lshl_or_b32 v107, s2, 14, v103
	v_add_u32_e32 v36, v107, v115
	v_add_u32_e32 v37, v107, v116
	v_add_u32_e32 v38, v107, v117
	v_add_u32_e32 v39, v107, v118
	v_add_u32_e32 v40, v107, v119
	v_add_u32_e32 v41, v107, v120
	ds_read_b128 v[132:135], v36
	ds_read_b128 v[136:139], v37
	ds_read_b128 v[140:143], v38
	ds_read_b128 v[144:147], v39
	ds_read_b128 v[148:151], v40
	ds_read_b128 v[152:155], v41
	ds_read_b128 v[156:159], v36 offset:8192
	ds_read_b128 v[160:163], v37 offset:8192
	ds_read_b128 v[164:167], v38 offset:8192
	ds_read_b128 v[168:171], v39 offset:8192
	ds_read_b128 v[172:175], v40 offset:8192
	ds_read_b128 v[176:179], v41 offset:8192
	v_lshl_add_u32 v114, s2, 13, v129
	s_waitcnt lgkmcnt(11)
	v_mfma_f32_32x32x16_bf16 v[52:67], v[132:135], v[68:71], 0
	s_waitcnt lgkmcnt(10)
	v_mfma_f32_32x32x16_bf16 v[52:67], v[136:139], v[72:75], v[52:67]
	s_waitcnt lgkmcnt(9)
	v_mfma_f32_32x32x16_bf16 v[52:67], v[140:143], v[76:79], v[52:67]
	s_waitcnt lgkmcnt(8)
	v_mfma_f32_32x32x16_bf16 v[52:67], v[144:147], v[80:83], v[52:67]
	s_waitcnt lgkmcnt(7)
	v_mfma_f32_32x32x16_bf16 v[52:67], v[148:151], v[84:87], v[52:67]
	s_waitcnt lgkmcnt(6)
	v_mfma_f32_32x32x16_bf16 v[52:67], v[152:155], v[88:91], v[52:67]
	s_waitcnt lgkmcnt(0)
	v_mfma_f32_32x32x16_bf16 v[36:51], v[156:159], v[68:71], 0
	v_add_u32_e32 v148, v114, v121
	v_add_u32_e32 v149, v114, v122
	ds_read_b64 v[132:133], v148
	ds_read_b64 v[134:135], v149
	v_mfma_f32_32x32x16_bf16 v[36:51], v[160:163], v[72:75], v[36:51]
	v_add_u32_e32 v150, v114, v123
	v_add_u32_e32 v151, v114, v124
	ds_read_b64 v[136:137], v150
	ds_read_b64 v[138:139], v151
	v_mfma_f32_32x32x16_bf16 v[36:51], v[164:167], v[76:79], v[36:51]
	v_add_u32_e32 v152, v114, v125
	v_add_u32_e32 v153, v114, v126
	ds_read_b64 v[140:141], v152
	ds_read_b64 v[142:143], v153
	v_mfma_f32_32x32x16_bf16 v[36:51], v[168:171], v[80:83], v[36:51]
	v_add_u32_e32 v154, v114, v127
	v_add_u32_e32 v155, v114, v128
	ds_read_b64 v[144:145], v154
	ds_read_b64 v[146:147], v155
	v_mfma_f32_32x32x16_bf16 v[36:51], v[172:175], v[84:87], v[36:51]
	v_mfma_f32_32x32x16_bf16 v[36:51], v[176:179], v[88:91], v[36:51]
	ds_read_b64 v[156:157], v152 offset:4096
	ds_read_b64 v[158:159], v153 offset:4096
	ds_read_b64 v[160:161], v154 offset:4096
	ds_read_b64 v[162:163], v155 offset:4096
	ds_read_b64 v[152:153], v150 offset:4096
	ds_read_b64 v[154:155], v151 offset:4096
	ds_read_b64 v[148:149], v148 offset:4096
	ds_read_b64 v[150:151], v149 offset:4096
	v_max3_f32 v107, v52, v53, v54
	v_max3_f32 v107, v107, v55, v56
	v_max3_f32 v107, v107, v57, v58
	v_max3_f32 v107, v107, v59, v60
	v_max3_f32 v107, v107, v61, v62
	v_max3_f32 v107, v107, v63, v64
	v_max3_f32 v107, v107, v65, v66
	v_max_f32_e32 v107, v107, v67
	v_max3_f32 v114, v36, v37, v38
	v_max3_f32 v114, v114, v39, v40
	v_max3_f32 v114, v114, v41, v42
	v_max3_f32 v114, v114, v43, v44
	v_max3_f32 v114, v114, v45, v46
	v_max3_f32 v114, v114, v47, v48
	v_max3_f32 v114, v114, v49, v50
	v_max3_f32 v107, v107, v114, v51
	v_mul_f32_e32 v107, s33, v107
	v_mov_b32_e32 v172, v107
	s_nop 1
	v_permlane32_swap_b32 v107, v172
	s_nop 1
	v_max3_f32 v107, v131, v107, v172
	v_sub_f32_e32 v114, v131, v107
	v_exp_f32_e32 v114, v114
	v_cmp_neq_f32_e32 vcc, v107, v131
	s_cbranch_vccz .Lat96_keep
	v_pk_mul_f32 v[34:35], v[34:35], v[114:115] op_sel_hi:[1,0]
	v_pk_mul_f32 v[32:33], v[32:33], v[114:115] op_sel_hi:[1,0]
	v_pk_mul_f32 v[30:31], v[30:31], v[114:115] op_sel_hi:[1,0]
	v_pk_mul_f32 v[28:29], v[28:29], v[114:115] op_sel_hi:[1,0]
	v_pk_mul_f32 v[26:27], v[26:27], v[114:115] op_sel_hi:[1,0]
	v_pk_mul_f32 v[24:25], v[24:25], v[114:115] op_sel_hi:[1,0]
	v_pk_mul_f32 v[22:23], v[22:23], v[114:115] op_sel_hi:[1,0]
	v_pk_mul_f32 v[20:21], v[20:21], v[114:115] op_sel_hi:[1,0]
	v_pk_mul_f32 v[18:19], v[18:19], v[114:115] op_sel_hi:[1,0]
	v_pk_mul_f32 v[16:17], v[16:17], v[114:115] op_sel_hi:[1,0]
	v_pk_mul_f32 v[14:15], v[14:15], v[114:115] op_sel_hi:[1,0]
	v_pk_mul_f32 v[12:13], v[12:13], v[114:115] op_sel_hi:[1,0]
	v_pk_mul_f32 v[10:11], v[10:11], v[114:115] op_sel_hi:[1,0]
	v_pk_mul_f32 v[8:9], v[8:9], v[114:115] op_sel_hi:[1,0]
	v_pk_mul_f32 v[6:7], v[6:7], v[114:115] op_sel_hi:[1,0]
	v_pk_mul_f32 v[4:5], v[4:5], v[114:115] op_sel_hi:[1,0]
.Lat96_keep:
	v_fma_f32 v52, v52, s33, -v107
	v_fma_f32 v53, v53, s33, -v107
	v_fma_f32 v54, v54, s33, -v107
	v_fma_f32 v55, v55, s33, -v107
	v_fma_f32 v56, v56, s33, -v107
	v_fma_f32 v57, v57, s33, -v107
	v_fma_f32 v58, v58, s33, -v107
	v_fma_f32 v59, v59, s33, -v107
	v_exp_f32_e32 v52, v52
	v_exp_f32_e32 v53, v53
	v_exp_f32_e32 v54, v54
	v_exp_f32_e32 v55, v55
	v_exp_f32_e32 v56, v56
	v_exp_f32_e32 v57, v57
	v_exp_f32_e32 v58, v58
	v_exp_f32_e32 v59, v59
	v_cvt_pk_bf16_f32 v164, v52, v53
	v_cvt_pk_bf16_f32 v165, v54, v55
	v_cvt_pk_bf16_f32 v166, v56, v57
	v_cvt_pk_bf16_f32 v167, v58, v59
	v_add_f32_e32 v52, v52, v53
	v_add_f32_e32 v54, v54, v55
	v_add_f32_e32 v56, v56, v57
	v_add_f32_e32 v58, v58, v59
	v_add_f32_e32 v52, v52, v54
	v_add_f32_e32 v56, v56, v58
	v_add_f32_e32 v52, v52, v56
	v_fma_f32 v60, v60, s33, -v107
	v_fma_f32 v61, v61, s33, -v107
	v_fma_f32 v62, v62, s33, -v107
	v_fma_f32 v63, v63, s33, -v107
	v_fma_f32 v64, v64, s33, -v107
	v_fma_f32 v65, v65, s33, -v107
	v_fma_f32 v66, v66, s33, -v107
	v_fma_f32 v67, v67, s33, -v107
	v_exp_f32_e32 v60, v60
	v_exp_f32_e32 v61, v61
	v_exp_f32_e32 v62, v62
	v_exp_f32_e32 v63, v63
	v_exp_f32_e32 v64, v64
	v_exp_f32_e32 v65, v65
	v_exp_f32_e32 v66, v66
	v_exp_f32_e32 v67, v67
	v_cvt_pk_bf16_f32 v168, v60, v61
	v_cvt_pk_bf16_f32 v169, v62, v63
	v_cvt_pk_bf16_f32 v170, v64, v65
	v_cvt_pk_bf16_f32 v171, v66, v67
	v_add_f32_e32 v60, v60, v61
	v_add_f32_e32 v62, v62, v63
	v_add_f32_e32 v64, v64, v65
	v_add_f32_e32 v66, v66, v67
	v_add_f32_e32 v60, v60, v62
	v_add_f32_e32 v64, v64, v66
	v_add_f32_e32 v60, v60, v64
	s_waitcnt lgkmcnt(0)
	v_mfma_f32_32x32x16_bf16 v[20:35], v[132:135], v[164:167], v[20:35]
	v_fma_f32 v36, v36, s33, -v107
	v_fma_f32 v37, v37, s33, -v107
	v_fma_f32 v38, v38, s33, -v107
	v_fma_f32 v39, v39, s33, -v107
	v_fma_f32 v40, v40, s33, -v107
	v_fma_f32 v41, v41, s33, -v107
	v_fma_f32 v42, v42, s33, -v107
	v_fma_f32 v43, v43, s33, -v107
	v_mfma_f32_32x32x16_bf16 v[4:19], v[148:151], v[164:167], v[4:19]
	v_exp_f32_e32 v36, v36
	v_exp_f32_e32 v37, v37
	v_exp_f32_e32 v38, v38
	v_exp_f32_e32 v39, v39
	v_exp_f32_e32 v40, v40
	v_exp_f32_e32 v41, v41
	v_exp_f32_e32 v42, v42
	v_exp_f32_e32 v43, v43
	v_mfma_f32_32x32x16_bf16 v[20:35], v[136:139], v[168:171], v[20:35]
	v_cvt_pk_bf16_f32 v172, v36, v37
	v_cvt_pk_bf16_f32 v173, v38, v39
	v_cvt_pk_bf16_f32 v174, v40, v41
	v_cvt_pk_bf16_f32 v175, v42, v43
	v_add_f32_e32 v36, v36, v37
	v_add_f32_e32 v38, v38, v39
	v_add_f32_e32 v40, v40, v41
	v_add_f32_e32 v42, v42, v43
	v_add_f32_e32 v36, v36, v38
	v_add_f32_e32 v40, v40, v42
	v_add_f32_e32 v36, v36, v40
	v_mfma_f32_32x32x16_bf16 v[4:19], v[152:155], v[168:171], v[4:19]
	v_fma_f32 v44, v44, s33, -v107
	v_fma_f32 v45, v45, s33, -v107
	v_fma_f32 v46, v46, s33, -v107
	v_fma_f32 v47, v47, s33, -v107
	v_fma_f32 v48, v48, s33, -v107
	v_fma_f32 v49, v49, s33, -v107
	v_fma_f32 v50, v50, s33, -v107
	v_fma_f32 v51, v51, s33, -v107
	v_exp_f32_e32 v44, v44
	v_exp_f32_e32 v45, v45
	v_exp_f32_e32 v46, v46
	v_exp_f32_e32 v47, v47
	v_exp_f32_e32 v48, v48
	v_exp_f32_e32 v49, v49
	v_exp_f32_e32 v50, v50
	v_exp_f32_e32 v51, v51
	v_cvt_pk_bf16_f32 v176, v44, v45
	v_cvt_pk_bf16_f32 v177, v46, v47
	v_cvt_pk_bf16_f32 v178, v48, v49
	v_cvt_pk_bf16_f32 v179, v50, v51
	v_add_f32_e32 v44, v44, v45
	v_add_f32_e32 v46, v46, v47
	v_add_f32_e32 v48, v48, v49
	v_add_f32_e32 v50, v50, v51
	v_add_f32_e32 v44, v44, v46
	v_add_f32_e32 v48, v48, v50
	v_add_f32_e32 v44, v44, v48
	v_add_f32_e32 v52, v52, v60
	v_add_f32_e32 v36, v36, v44
	v_add_f32_e32 v52, v52, v36
	v_fma_f32 v36, v130, v114, v52
	v_mfma_f32_32x32x16_bf16 v[20:35], v[140:143], v[172:175], v[20:35]
	v_mfma_f32_32x32x16_bf16 v[4:19], v[156:159], v[172:175], v[4:19]
	v_mfma_f32_32x32x16_bf16 v[20:35], v[144:147], v[176:179], v[20:35]
	v_mfma_f32_32x32x16_bf16 v[4:19], v[160:163], v[176:179], v[4:19]
	s_add_i32 s27, s27, 1
	s_add_i32 s26, s26, -1
	s_cmp_lg_u32 s26, -1
	s_cbranch_scc1 .LBB0_373

.LBB0_402:
	v_or_b32_e32 v2, s36, v10
	v_add_u32_e32 v2, s94, v2
	v_lshrrev_b32_e32 v5, 6, v2
	v_med3_u32 v5, v5, 4, 60
	v_add_u32_e32 v99, -4, v5
	v_add_u32_e32 v100, 4, v5
	v_lshrrev_b32_e32 v5, 1, v8
	v_bfe_u32 v7, v8, 1, 3
	v_bitop3_b32 v5, v9, v5, 7 bitop3:0x78
	v_lshlrev_b32_e32 v102, 4, v5
	v_bitop3_b32 v5, v9, v7, 2 bitop3:0x36
	v_and_b32_e32 v2, 63, v2
	v_lshlrev_b32_e32 v103, 4, v5
	v_bitop3_b32 v5, v9, v7, 4 bitop3:0x36
	v_med3_u32 v2, v2, 8, 56
	v_lshlrev_b32_e32 v104, 4, v5
	v_bitop3_b32 v5, v9, v7, 6 bitop3:0x36
	v_add_u32_e32 v6, -8, v2
	v_lshlrev_b32_e32 v105, 4, v5
	v_or_b32_e32 v5, 1, v98
	v_cmp_ge_u32_e64 s[4:5], v5, v6
	v_or_b32_e32 v5, 2, v98
	v_cmp_ge_u32_e64 s[6:7], v5, v6
	v_or_b32_e32 v5, 3, v98
	v_cmp_ge_u32_e64 s[8:9], v5, v6
	v_or_b32_e32 v5, 8, v98
	v_cmp_ge_u32_e64 s[10:11], v5, v6
	v_or_b32_e32 v5, 9, v98
	v_cmp_ge_u32_e64 s[12:13], v5, v6
	v_or_b32_e32 v5, 10, v98
	v_cmp_ge_u32_e64 s[14:15], v5, v6
	v_or_b32_e32 v5, 11, v98
	v_add_u32_e32 v2, 8, v2
	v_cmp_ge_u32_e64 s[16:17], v5, v6
	v_or_b32_e32 v5, 16, v98
	v_cmp_ge_u32_e32 vcc, v5, v6
	v_cmp_lt_u32_e64 s[18:19], v5, v2
	v_or_b32_e32 v5, 17, v98
	s_and_b64 s[52:53], vcc, s[18:19]
	v_cmp_ge_u32_e32 vcc, v5, v6
	v_cmp_lt_u32_e64 s[18:19], v5, v2
	v_or_b32_e32 v5, 18, v98
	s_and_b64 s[54:55], vcc, s[18:19]
	v_cmp_ge_u32_e32 vcc, v5, v6
	v_cmp_lt_u32_e64 s[18:19], v5, v2
	v_or_b32_e32 v5, 19, v98
	s_and_b64 s[56:57], vcc, s[18:19]
	v_cmp_ge_u32_e32 vcc, v5, v6
	v_cmp_lt_u32_e64 s[18:19], v5, v2
	v_or_b32_e32 v5, 24, v98
	s_and_b64 s[58:59], vcc, s[18:19]
	v_cmp_ge_u32_e32 vcc, v5, v6
	v_cmp_lt_u32_e64 s[18:19], v5, v2
	v_or_b32_e32 v5, 25, v98
	s_and_b64 s[60:61], vcc, s[18:19]
	v_cmp_ge_u32_e32 vcc, v5, v6
	v_cmp_lt_u32_e64 s[18:19], v5, v2
	v_or_b32_e32 v5, 26, v98
	s_and_b64 s[62:63], vcc, s[18:19]
	v_cmp_ge_u32_e32 vcc, v5, v6
	v_cmp_lt_u32_e64 s[18:19], v5, v2
	v_or_b32_e32 v5, 27, v98
	s_and_b64 s[64:65], vcc, s[18:19]
	v_cmp_ge_u32_e32 vcc, v5, v6
	v_cmp_lt_u32_e64 s[18:19], v5, v2
	v_or_b32_e32 v5, 32, v98
	s_and_b64 s[66:67], vcc, s[18:19]
	v_cmp_ge_u32_e32 vcc, v5, v6
	v_cmp_lt_u32_e64 s[18:19], v5, v2
	v_or_b32_e32 v5, 33, v98
	s_and_b64 s[68:69], vcc, s[18:19]
	v_cmp_ge_u32_e32 vcc, v5, v6
	v_cmp_lt_u32_e64 s[18:19], v5, v2
	v_or_b32_e32 v5, 34, v98
	s_and_b64 s[70:71], vcc, s[18:19]
	v_cmp_ge_u32_e32 vcc, v5, v6
	v_cmp_lt_u32_e64 s[18:19], v5, v2
	v_or_b32_e32 v5, 35, v98
	s_and_b64 s[72:73], vcc, s[18:19]
	v_cmp_ge_u32_e32 vcc, v5, v6
	v_cmp_lt_u32_e64 s[18:19], v5, v2
	v_or_b32_e32 v5, 40, v98
	s_and_b64 s[74:75], vcc, s[18:19]
	v_cmp_ge_u32_e32 vcc, v5, v6
	v_cmp_lt_u32_e64 s[18:19], v5, v2
	v_or_b32_e32 v5, 41, v98
	s_and_b64 s[76:77], vcc, s[18:19]
	v_cmp_ge_u32_e32 vcc, v5, v6
	v_cmp_lt_u32_e64 s[18:19], v5, v2
	v_or_b32_e32 v5, 42, v98
	s_and_b64 s[78:79], vcc, s[18:19]
	v_cmp_ge_u32_e32 vcc, v5, v6
	v_cmp_lt_u32_e64 s[18:19], v5, v2
	v_or_b32_e32 v5, 43, v98
	s_and_b64 s[38:39], vcc, s[18:19]
	v_cmp_ge_u32_e32 vcc, v5, v6
	v_cmp_lt_u32_e64 s[18:19], v5, v2
	v_or_b32_e32 v5, 48, v98
	s_and_b64 s[42:43], vcc, s[18:19]
	v_cmp_lt_u32_e64 s[18:19], v5, v2
	v_or_b32_e32 v5, 49, v98
	v_cmp_lt_u32_e64 s[20:21], v5, v2
	v_or_b32_e32 v5, 50, v98
	v_cmp_lt_u32_e64 s[22:23], v5, v2
	v_or_b32_e32 v5, 51, v98
	v_cmp_ge_u32_e64 s[2:3], v98, v6
	v_cmp_lt_u32_e64 s[24:25], v5, v2
	v_or_b32_e32 v5, 56, v98
	v_writelane_b32 v251, s2, 58
	v_cmp_lt_u32_e64 s[26:27], v5, v2
	v_or_b32_e32 v5, 57, v98
	v_lshlrev_b32_e32 v101, 7, v10
	v_writelane_b32 v251, s3, 59
	v_cmp_lt_u32_e64 s[28:29], v5, v2
	v_or_b32_e32 v5, 58, v98
	s_mov_b32 s2, 0x10000
	v_cmp_lt_u32_e64 s[30:31], v5, v2
	v_or_b32_e32 v5, 59, v98
	v_or3_b32 v114, v101, v4, s2
	s_add_i32 s2, s36, s94
	v_cmp_lt_u32_e64 s[34:35], v5, v2
	v_add_u32_e32 v2, s2, v10
	s_sub_i32 s90, s37, s44
	v_lshrrev_b32_e32 v2, 6, v2
	v_sub_u32_e32 v2, s90, v2
	s_movk_i32 s2, 0x7c
	v_mul_lo_u32 v2, v2, s2
	s_lshr_b32 s2, s49, 1
	s_and_b32 s2, s2, 0xffe0
	v_bitop3_b16 v4, s2, v8, 31 bitop3:0xf8
	v_and_b32_e32 v4, 63, v4
	v_lshl_add_u32 v2, v9, 4, v2
	v_lshlrev_b32_e32 v4, 2, v4
	v_sub_u32_e32 v2, v2, v4
	v_mov_b32_e32 v16, v3
	v_mov_b32_e32 v17, v3
	v_lshlrev_b32_e32 v106, 4, v7
	v_add_u32_e32 v115, 0x183a0, v2
	v_mov_b32_e32 v2, v3
	v_mov_b32_e32 v4, v3
	v_mov_b32_e32 v5, v3
	v_mov_b32_e32 v6, v3
	v_mov_b32_e32 v7, v3
	v_mov_b32_e32 v8, v3
	v_mov_b32_e32 v9, v3
	v_mov_b32_e32 v10, v3
	v_mov_b32_e32 v11, v3
	v_mov_b32_e32 v12, v3
	v_mov_b32_e32 v13, v3
	v_mov_b32_e32 v14, v3
	v_mov_b32_e32 v15, v3
	v_mov_b64_e32 v[34:35], v[16:17]
	v_mov_b64_e32 v[32:33], v[14:15]
	v_mov_b64_e32 v[30:31], v[12:13]
	v_mov_b64_e32 v[28:29], v[10:11]
	v_mov_b64_e32 v[26:27], v[8:9]
	v_mov_b64_e32 v[24:25], v[6:7]
	v_mov_b64_e32 v[22:23], v[4:5]
	v_mov_b64_e32 v[20:21], v[2:3]
	v_mov_b64_e32 v[18:19], v[16:17]
	s_add_i32 s40, s41, -3
	v_xor_b32_e32 v107, 16, v106
	v_xor_b32_e32 v108, 32, v106
	v_xor_b32_e32 v109, 48, v106
	v_xor_b32_e32 v110, 64, v106
	v_xor_b32_e32 v111, 0x50, v106
	v_xor_b32_e32 v112, 0x60, v106
	v_xor_b32_e32 v113, 0x70, v106
	s_add_i32 s41, s41, -1
	s_mov_b32 s49, 0
	v_mov_b32_e32 v94, 0xf149f2ca
	v_mov_b32_e32 v116, 0
	v_mov_b64_e32 v[16:17], v[14:15]
	v_mov_b64_e32 v[14:15], v[12:13]
	v_mov_b64_e32 v[12:13], v[10:11]
	v_mov_b64_e32 v[10:11], v[8:9]
	v_mov_b64_e32 v[8:9], v[6:7]
	v_mov_b64_e32 v[6:7], v[4:5]
	v_mov_b64_e32 v[4:5], v[2:3]
	s_waitcnt vmcnt(0)
	s_branch .LBB0_405
.LBB0_404:
	s_or_b64 exec, exec, s[36:37]
	s_add_i32 s49, s49, 1
	s_add_i32 s41, s41, -1
	s_cmp_eq_u32 s41, -1
	v_add_u32_e32 v115, 0x7c, v115
	s_movk_i32 s95, 0x2000
	s_cbranch_scc1 .LBB0_488

.LBB0_417:
	s_and_saveexec_b64 s[36:37], s[96:97]
	s_cbranch_execz .LBB0_404
	s_andn2_b64 vcc, exec, s[94:95]
	s_cbranch_vccz .Lat64_fast
	s_and_b32 s2, s49, 3
	v_lshl_or_b32 v2, s2, 14, v101
	v_add_u32_e32 v36, v2, v102
	v_add_u32_e32 v37, v2, v103
	v_add_u32_e32 v38, v2, v104
	v_add_u32_e32 v39, v2, v105
	ds_read_b128 v[118:121], v36
	ds_read_b128 v[122:125], v37
	ds_read_b128 v[126:129], v38
	ds_read_b128 v[130:133], v39
	ds_read_b128 v[134:137], v36 offset:4096
	ds_read_b128 v[138:141], v37 offset:4096
	ds_read_b128 v[142:145], v38 offset:4096
	ds_read_b128 v[146:149], v39 offset:4096
	v_lshl_add_u32 v170, s2, 13, v114
	s_waitcnt lgkmcnt(7)
	v_mfma_f32_32x32x16_bf16 v[52:67], v[118:121], v[68:71], 0
	s_waitcnt lgkmcnt(6)
	v_mfma_f32_32x32x16_bf16 v[52:67], v[122:125], v[72:75], v[52:67]
	s_waitcnt lgkmcnt(5)
	v_mfma_f32_32x32x16_bf16 v[52:67], v[126:129], v[76:79], v[52:67]
	s_waitcnt lgkmcnt(4)
	v_mfma_f32_32x32x16_bf16 v[52:67], v[130:133], v[80:83], v[52:67]
	s_waitcnt lgkmcnt(0)
	v_mfma_f32_32x32x16_bf16 v[36:51], v[134:137], v[68:71], 0
	v_mfma_f32_32x32x16_bf16 v[36:51], v[138:141], v[72:75], v[36:51]
	v_mfma_f32_32x32x16_bf16 v[36:51], v[142:145], v[76:79], v[36:51]
	v_mfma_f32_32x32x16_bf16 v[36:51], v[146:149], v[80:83], v[36:51]
	ds_read_b32 v118, v115 offset:0
	ds_read_b32 v119, v115 offset:4
	ds_read_b32 v120, v115 offset:8
	ds_read_b32 v121, v115 offset:12
	ds_read_b32 v122, v115 offset:32
	ds_read_b32 v123, v115 offset:36
	ds_read_b32 v124, v115 offset:40
	ds_read_b32 v125, v115 offset:44
	ds_read_b32 v126, v115 offset:64
	ds_read_b32 v127, v115 offset:68
	ds_read_b32 v128, v115 offset:72
	ds_read_b32 v129, v115 offset:76
	ds_read_b32 v130, v115 offset:96
	ds_read_b32 v131, v115 offset:100
	ds_read_b32 v132, v115 offset:104
	ds_read_b32 v133, v115 offset:108
	ds_read_b32 v134, v115 offset:128
	ds_read_b32 v135, v115 offset:132
	ds_read_b32 v136, v115 offset:136
	ds_read_b32 v137, v115 offset:140
	ds_read_b32 v138, v115 offset:160
	ds_read_b32 v139, v115 offset:164
	ds_read_b32 v140, v115 offset:168
	ds_read_b32 v141, v115 offset:172
	ds_read_b32 v142, v115 offset:192
	ds_read_b32 v143, v115 offset:196
	ds_read_b32 v144, v115 offset:200
	ds_read_b32 v145, v115 offset:204
	ds_read_b32 v146, v115 offset:224
	ds_read_b32 v147, v115 offset:228
	ds_read_b32 v148, v115 offset:232
	ds_read_b32 v149, v115 offset:236
	v_and_b32_e32 v173, 31, v0
	v_bfe_u32 v174, v0, 6, 1
	v_lshl_or_b32 v173, v174, 5, v173
	v_max_u32_e32 v173, 8, v173
	v_min_u32_e32 v173, 56, v173
	v_bfe_u32 v174, v0, 5, 1
	v_lshl_add_u32 v174, v174, 2, 8
	v_sub_u32_e32 v173, v174, v173
	v_mov_b32_e32 v171, 0x3e38aa3b
	v_mov_b32_e32 v172, 0xf149f2ca
	s_waitcnt lgkmcnt(0)
	v_add_u32_e32 v150, 0, v173
	v_add_u32_e32 v151, 1, v173
	v_add_u32_e32 v152, 2, v173
	v_add_u32_e32 v153, 3, v173
	v_cmp_gt_u32_e64 vcc, 16, v150
	v_cmp_gt_u32_e64 s[2:3], 16, v151
	v_cmp_gt_u32_e64 s[98:99], 16, v152
	v_cmp_gt_u32_e64 s[100:101], 16, v153
	v_fma_f32 v52, v52, v171, v118
	v_fma_f32 v53, v53, v171, v119
	v_fma_f32 v54, v54, v171, v120
	v_fma_f32 v55, v55, v171, v121
	v_cndmask_b32_e64 v52, v172, v52, vcc
	v_cndmask_b32_e64 v53, v172, v53, s[2:3]
	v_cndmask_b32_e64 v54, v172, v54, s[98:99]
	v_cndmask_b32_e64 v55, v172, v55, s[100:101]
	v_add_u32_e32 v150, 8, v173
	v_add_u32_e32 v151, 9, v173
	v_add_u32_e32 v152, 10, v173
	v_add_u32_e32 v153, 11, v173
	v_cmp_gt_u32_e64 vcc, 16, v150
	v_cmp_gt_u32_e64 s[2:3], 16, v151
	v_cmp_gt_u32_e64 s[98:99], 16, v152
	v_cmp_gt_u32_e64 s[100:101], 16, v153
	v_fma_f32 v56, v56, v171, v122
	v_fma_f32 v57, v57, v171, v123
	v_fma_f32 v58, v58, v171, v124
	v_fma_f32 v59, v59, v171, v125
	v_cndmask_b32_e64 v56, v172, v56, vcc
	v_cndmask_b32_e64 v57, v172, v57, s[2:3]
	v_cndmask_b32_e64 v58, v172, v58, s[98:99]
	v_cndmask_b32_e64 v59, v172, v59, s[100:101]
	v_add_u32_e32 v150, 16, v173
	v_add_u32_e32 v151, 17, v173
	v_add_u32_e32 v152, 18, v173
	v_add_u32_e32 v153, 19, v173
	v_cmp_gt_u32_e64 vcc, 16, v150
	v_cmp_gt_u32_e64 s[2:3], 16, v151
	v_cmp_gt_u32_e64 s[98:99], 16, v152
	v_cmp_gt_u32_e64 s[100:101], 16, v153
	v_fma_f32 v60, v60, v171, v126
	v_fma_f32 v61, v61, v171, v127
	v_fma_f32 v62, v62, v171, v128
	v_fma_f32 v63, v63, v171, v129
	v_cndmask_b32_e64 v60, v172, v60, vcc
	v_cndmask_b32_e64 v61, v172, v61, s[2:3]
	v_cndmask_b32_e64 v62, v172, v62, s[98:99]
	v_cndmask_b32_e64 v63, v172, v63, s[100:101]
	v_add_u32_e32 v150, 24, v173
	v_add_u32_e32 v151, 25, v173
	v_add_u32_e32 v152, 26, v173
	v_add_u32_e32 v153, 27, v173
	v_cmp_gt_u32_e64 vcc, 16, v150
	v_cmp_gt_u32_e64 s[2:3], 16, v151
	v_cmp_gt_u32_e64 s[98:99], 16, v152
	v_cmp_gt_u32_e64 s[100:101], 16, v153
	v_fma_f32 v64, v64, v171, v130
	v_fma_f32 v65, v65, v171, v131
	v_fma_f32 v66, v66, v171, v132
	v_fma_f32 v67, v67, v171, v133
	v_cndmask_b32_e64 v64, v172, v64, vcc
	v_cndmask_b32_e64 v65, v172, v65, s[2:3]
	v_cndmask_b32_e64 v66, v172, v66, s[98:99]
	v_cndmask_b32_e64 v67, v172, v67, s[100:101]
	v_add_u32_e32 v150, 32, v173
	v_add_u32_e32 v151, 33, v173
	v_add_u32_e32 v152, 34, v173
	v_add_u32_e32 v153, 35, v173
	v_cmp_gt_u32_e64 vcc, 16, v150
	v_cmp_gt_u32_e64 s[2:3], 16, v151
	v_cmp_gt_u32_e64 s[98:99], 16, v152
	v_cmp_gt_u32_e64 s[100:101], 16, v153
	v_fma_f32 v36, v36, v171, v134
	v_fma_f32 v37, v37, v171, v135
	v_fma_f32 v38, v38, v171, v136
	v_fma_f32 v39, v39, v171, v137
	v_cndmask_b32_e64 v36, v172, v36, vcc
	v_cndmask_b32_e64 v37, v172, v37, s[2:3]
	v_cndmask_b32_e64 v38, v172, v38, s[98:99]
	v_cndmask_b32_e64 v39, v172, v39, s[100:101]
	v_add_u32_e32 v150, 40, v173
	v_add_u32_e32 v151, 41, v173
	v_add_u32_e32 v152, 42, v173
	v_add_u32_e32 v153, 43, v173
	v_cmp_gt_u32_e64 vcc, 16, v150
	v_cmp_gt_u32_e64 s[2:3], 16, v151
	v_cmp_gt_u32_e64 s[98:99], 16, v152
	v_cmp_gt_u32_e64 s[100:101], 16, v153
	v_fma_f32 v40, v40, v171, v138
	v_fma_f32 v41, v41, v171, v139
	v_fma_f32 v42, v42, v171, v140
	v_fma_f32 v43, v43, v171, v141
	v_cndmask_b32_e64 v40, v172, v40, vcc
	v_cndmask_b32_e64 v41, v172, v41, s[2:3]
	v_cndmask_b32_e64 v42, v172, v42, s[98:99]
	v_cndmask_b32_e64 v43, v172, v43, s[100:101]
	v_add_u32_e32 v150, 48, v173
	v_add_u32_e32 v151, 49, v173
	v_add_u32_e32 v152, 50, v173
	v_add_u32_e32 v153, 51, v173
	v_cmp_gt_u32_e64 vcc, 16, v150
	v_cmp_gt_u32_e64 s[2:3], 16, v151
	v_cmp_gt_u32_e64 s[98:99], 16, v152
	v_cmp_gt_u32_e64 s[100:101], 16, v153
	v_fma_f32 v44, v44, v171, v142
	v_fma_f32 v45, v45, v171, v143
	v_fma_f32 v46, v46, v171, v144
	v_fma_f32 v47, v47, v171, v145
	v_cndmask_b32_e64 v44, v172, v44, vcc
	v_cndmask_b32_e64 v45, v172, v45, s[2:3]
	v_cndmask_b32_e64 v46, v172, v46, s[98:99]
	v_cndmask_b32_e64 v47, v172, v47, s[100:101]
	v_add_u32_e32 v150, 56, v173
	v_add_u32_e32 v151, 57, v173
	v_add_u32_e32 v152, 58, v173
	v_add_u32_e32 v153, 59, v173
	v_cmp_gt_u32_e64 vcc, 16, v150
	v_cmp_gt_u32_e64 s[2:3], 16, v151
	v_cmp_gt_u32_e64 s[98:99], 16, v152
	v_cmp_gt_u32_e64 s[100:101], 16, v153
	v_fma_f32 v48, v48, v171, v146
	v_fma_f32 v49, v49, v171, v147
	v_fma_f32 v50, v50, v171, v148
	v_fma_f32 v51, v51, v171, v149
	v_cndmask_b32_e64 v48, v172, v48, vcc
	v_cndmask_b32_e64 v49, v172, v49, s[2:3]
	v_cndmask_b32_e64 v50, v172, v50, s[98:99]
	v_cndmask_b32_e64 v51, v172, v51, s[100:101]
	v_add_u32_e32 v154, v170, v106
	v_add_u32_e32 v155, v170, v107
	v_add_u32_e32 v156, v170, v108
	v_add_u32_e32 v157, v170, v109
	v_add_u32_e32 v158, v170, v110
	v_add_u32_e32 v159, v170, v111
	v_add_u32_e32 v160, v170, v112
	v_add_u32_e32 v161, v170, v113
	ds_read_b64 v[118:119], v154
	ds_read_b64 v[120:121], v155
	ds_read_b64 v[122:123], v156
	ds_read_b64 v[124:125], v157
	ds_read_b64 v[126:127], v158
	ds_read_b64 v[128:129], v159
	ds_read_b64 v[130:131], v160
	ds_read_b64 v[132:133], v161
	ds_read_b64 v[142:143], v158 offset:4096
	ds_read_b64 v[144:145], v159 offset:4096
	ds_read_b64 v[146:147], v160 offset:4096
	ds_read_b64 v[148:149], v161 offset:4096
	ds_read_b64 v[138:139], v156 offset:4096
	ds_read_b64 v[140:141], v157 offset:4096
	ds_read_b64 v[134:135], v154 offset:4096
	ds_read_b64 v[136:137], v155 offset:4096
	v_max3_f32 v2, v52, v53, v54
	v_max3_f32 v2, v2, v55, v56
	v_max3_f32 v2, v2, v57, v58
	v_max3_f32 v2, v2, v59, v60
	v_max3_f32 v2, v2, v61, v62
	v_max3_f32 v2, v2, v63, v64
	v_max3_f32 v2, v2, v65, v66
	v_max_f32_e32 v2, v2, v67
	v_max3_f32 v170, v36, v37, v38
	v_max3_f32 v170, v170, v39, v40
	v_max3_f32 v170, v170, v41, v42
	v_max3_f32 v170, v170, v43, v44
	v_max3_f32 v170, v170, v45, v46
	v_max3_f32 v170, v170, v47, v48
	v_max3_f32 v170, v170, v49, v50
	v_max3_f32 v2, v2, v170, v51
	v_mov_b32_e32 v167, v2
	s_nop 1
	v_permlane32_swap_b32 v2, v167
	s_nop 1
	v_max3_f32 v166, v94, v2, v167
	v_sub_f32_e32 v168, v94, v166
	v_exp_f32_e32 v168, v168
	v_cmp_neq_f32_e32 vcc, v166, v94
	s_cbranch_vccz .Lat64b_keep
	v_pk_mul_f32 v[34:35], v[34:35], v[168:169] op_sel_hi:[1,0]
	v_pk_mul_f32 v[32:33], v[32:33], v[168:169] op_sel_hi:[1,0]
	v_pk_mul_f32 v[30:31], v[30:31], v[168:169] op_sel_hi:[1,0]
	v_pk_mul_f32 v[28:29], v[28:29], v[168:169] op_sel_hi:[1,0]
	v_pk_mul_f32 v[26:27], v[26:27], v[168:169] op_sel_hi:[1,0]
	v_pk_mul_f32 v[24:25], v[24:25], v[168:169] op_sel_hi:[1,0]
	v_pk_mul_f32 v[22:23], v[22:23], v[168:169] op_sel_hi:[1,0]
	v_pk_mul_f32 v[20:21], v[20:21], v[168:169] op_sel_hi:[1,0]
	v_pk_mul_f32 v[18:19], v[18:19], v[168:169] op_sel_hi:[1,0]
	v_pk_mul_f32 v[16:17], v[16:17], v[168:169] op_sel_hi:[1,0]
	v_pk_mul_f32 v[14:15], v[14:15], v[168:169] op_sel_hi:[1,0]
	v_pk_mul_f32 v[12:13], v[12:13], v[168:169] op_sel_hi:[1,0]
	v_pk_mul_f32 v[10:11], v[10:11], v[168:169] op_sel_hi:[1,0]
	v_pk_mul_f32 v[8:9], v[8:9], v[168:169] op_sel_hi:[1,0]
	v_pk_mul_f32 v[6:7], v[6:7], v[168:169] op_sel_hi:[1,0]
	v_pk_mul_f32 v[4:5], v[4:5], v[168:169] op_sel_hi:[1,0]
.Lat64b_keep:
	v_sub_f32_e32 v52, v52, v166
	v_sub_f32_e32 v53, v53, v166
	v_sub_f32_e32 v54, v54, v166
	v_sub_f32_e32 v55, v55, v166
	v_sub_f32_e32 v56, v56, v166
	v_sub_f32_e32 v57, v57, v166
	v_sub_f32_e32 v58, v58, v166
	v_sub_f32_e32 v59, v59, v166
	v_exp_f32_e32 v52, v52
	v_exp_f32_e32 v53, v53
	v_exp_f32_e32 v54, v54
	v_exp_f32_e32 v55, v55
	v_exp_f32_e32 v56, v56
	v_exp_f32_e32 v57, v57
	v_exp_f32_e32 v58, v58
	v_exp_f32_e32 v59, v59
	v_cvt_pk_bf16_f32 v150, v52, v53
	v_cvt_pk_bf16_f32 v151, v54, v55
	v_cvt_pk_bf16_f32 v152, v56, v57
	v_cvt_pk_bf16_f32 v153, v58, v59
	v_add_f32_e32 v52, v52, v53
	v_add_f32_e32 v54, v54, v55
	v_add_f32_e32 v56, v56, v57
	v_add_f32_e32 v58, v58, v59
	v_add_f32_e32 v52, v52, v54
	v_add_f32_e32 v56, v56, v58
	v_add_f32_e32 v52, v52, v56
	v_sub_f32_e32 v60, v60, v166
	v_sub_f32_e32 v61, v61, v166
	v_sub_f32_e32 v62, v62, v166
	v_sub_f32_e32 v63, v63, v166
	v_sub_f32_e32 v64, v64, v166
	v_sub_f32_e32 v65, v65, v166
	v_sub_f32_e32 v66, v66, v166
	v_sub_f32_e32 v67, v67, v166
	v_exp_f32_e32 v60, v60
	v_exp_f32_e32 v61, v61
	v_exp_f32_e32 v62, v62
	v_exp_f32_e32 v63, v63
	v_exp_f32_e32 v64, v64
	v_exp_f32_e32 v65, v65
	v_exp_f32_e32 v66, v66
	v_exp_f32_e32 v67, v67
	v_cvt_pk_bf16_f32 v154, v60, v61
	v_cvt_pk_bf16_f32 v155, v62, v63
	v_cvt_pk_bf16_f32 v156, v64, v65
	v_cvt_pk_bf16_f32 v157, v66, v67
	v_add_f32_e32 v60, v60, v61
	v_add_f32_e32 v62, v62, v63
	v_add_f32_e32 v64, v64, v65
	v_add_f32_e32 v66, v66, v67
	v_add_f32_e32 v60, v60, v62
	v_add_f32_e32 v64, v64, v66
	v_add_f32_e32 v60, v60, v64
	s_waitcnt lgkmcnt(0)
	v_mfma_f32_32x32x16_bf16 v[20:35], v[118:121], v[150:153], v[20:35]
	v_sub_f32_e32 v36, v36, v166
	v_sub_f32_e32 v37, v37, v166
	v_sub_f32_e32 v38, v38, v166
	v_sub_f32_e32 v39, v39, v166
	v_sub_f32_e32 v40, v40, v166
	v_sub_f32_e32 v41, v41, v166
	v_sub_f32_e32 v42, v42, v166
	v_sub_f32_e32 v43, v43, v166
	v_mfma_f32_32x32x16_bf16 v[4:19], v[134:137], v[150:153], v[4:19]
	v_exp_f32_e32 v36, v36
	v_exp_f32_e32 v37, v37
	v_exp_f32_e32 v38, v38
	v_exp_f32_e32 v39, v39
	v_exp_f32_e32 v40, v40
	v_exp_f32_e32 v41, v41
	v_exp_f32_e32 v42, v42
	v_exp_f32_e32 v43, v43
	v_mfma_f32_32x32x16_bf16 v[20:35], v[122:125], v[154:157], v[20:35]
	v_cvt_pk_bf16_f32 v158, v36, v37
	v_cvt_pk_bf16_f32 v159, v38, v39
	v_cvt_pk_bf16_f32 v160, v40, v41
	v_cvt_pk_bf16_f32 v161, v42, v43
	v_add_f32_e32 v36, v36, v37
	v_add_f32_e32 v38, v38, v39
	v_add_f32_e32 v40, v40, v41
	v_add_f32_e32 v42, v42, v43
	v_add_f32_e32 v36, v36, v38
	v_add_f32_e32 v40, v40, v42
	v_add_f32_e32 v36, v36, v40
	v_mfma_f32_32x32x16_bf16 v[4:19], v[138:141], v[154:157], v[4:19]
	v_sub_f32_e32 v44, v44, v166
	v_sub_f32_e32 v45, v45, v166
	v_sub_f32_e32 v46, v46, v166
	v_sub_f32_e32 v47, v47, v166
	v_sub_f32_e32 v48, v48, v166
	v_sub_f32_e32 v49, v49, v166
	v_sub_f32_e32 v50, v50, v166
	v_sub_f32_e32 v51, v51, v166
	v_exp_f32_e32 v44, v44
	v_exp_f32_e32 v45, v45
	v_exp_f32_e32 v46, v46
	v_exp_f32_e32 v47, v47
	v_exp_f32_e32 v48, v48
	v_exp_f32_e32 v49, v49
	v_exp_f32_e32 v50, v50
	v_exp_f32_e32 v51, v51
	v_cvt_pk_bf16_f32 v162, v44, v45
	v_cvt_pk_bf16_f32 v163, v46, v47
	v_cvt_pk_bf16_f32 v164, v48, v49
	v_cvt_pk_bf16_f32 v165, v50, v51
	v_add_f32_e32 v44, v44, v45
	v_add_f32_e32 v46, v46, v47
	v_add_f32_e32 v48, v48, v49
	v_add_f32_e32 v50, v50, v51
	v_add_f32_e32 v44, v44, v46
	v_add_f32_e32 v48, v48, v50
	v_add_f32_e32 v44, v44, v48
	v_add_f32_e32 v52, v52, v60
	v_add_f32_e32 v36, v36, v44
	v_add_f32_e32 v52, v52, v36
	v_fma_f32 v116, v116, v168, v52
	v_mfma_f32_32x32x16_bf16 v[20:35], v[126:129], v[158:161], v[20:35]
	v_mfma_f32_32x32x16_bf16 v[4:19], v[142:145], v[158:161], v[4:19]
	v_mfma_f32_32x32x16_bf16 v[20:35], v[130:133], v[162:165], v[20:35]
	v_mfma_f32_32x32x16_bf16 v[4:19], v[146:149], v[162:165], v[4:19]
	v_mov_b32_e32 v94, v166
	s_branch .LBB0_404
.Lat64_fast:
	s_and_b32 s2, s49, 3
	v_lshl_or_b32 v2, s2, 14, v101
	v_add_u32_e32 v36, v2, v102
	v_add_u32_e32 v37, v2, v103
	v_add_u32_e32 v38, v2, v104
	v_add_u32_e32 v39, v2, v105
	ds_read_b128 v[118:121], v36
	ds_read_b128 v[122:125], v37
	ds_read_b128 v[126:129], v38
	ds_read_b128 v[130:133], v39
	ds_read_b128 v[134:137], v36 offset:4096
	ds_read_b128 v[138:141], v37 offset:4096
	ds_read_b128 v[142:145], v38 offset:4096
	ds_read_b128 v[146:149], v39 offset:4096
	v_lshl_add_u32 v170, s2, 13, v114
	s_waitcnt lgkmcnt(7)
	v_mfma_f32_32x32x16_bf16 v[52:67], v[118:121], v[68:71], 0
	s_waitcnt lgkmcnt(6)
	v_mfma_f32_32x32x16_bf16 v[52:67], v[122:125], v[72:75], v[52:67]
	s_waitcnt lgkmcnt(5)
	v_mfma_f32_32x32x16_bf16 v[52:67], v[126:129], v[76:79], v[52:67]
	s_waitcnt lgkmcnt(4)
	v_mfma_f32_32x32x16_bf16 v[52:67], v[130:133], v[80:83], v[52:67]
	s_waitcnt lgkmcnt(0)
	v_mfma_f32_32x32x16_bf16 v[36:51], v[134:137], v[68:71], 0
	v_add_u32_e32 v154, v170, v106
	v_add_u32_e32 v155, v170, v107
	ds_read_b64 v[118:119], v154
	ds_read_b64 v[120:121], v155
	v_mfma_f32_32x32x16_bf16 v[36:51], v[138:141], v[72:75], v[36:51]
	v_add_u32_e32 v156, v170, v108
	v_add_u32_e32 v157, v170, v109
	ds_read_b64 v[122:123], v156
	ds_read_b64 v[124:125], v157
	v_mfma_f32_32x32x16_bf16 v[36:51], v[142:145], v[76:79], v[36:51]
	v_add_u32_e32 v158, v170, v110
	v_add_u32_e32 v159, v170, v111
	ds_read_b64 v[126:127], v158
	ds_read_b64 v[128:129], v159
	v_mfma_f32_32x32x16_bf16 v[36:51], v[146:149], v[80:83], v[36:51]
	v_add_u32_e32 v160, v170, v112
	v_add_u32_e32 v161, v170, v113
	ds_read_b64 v[130:131], v160
	ds_read_b64 v[132:133], v161
	ds_read_b64 v[142:143], v158 offset:4096
	ds_read_b64 v[144:145], v159 offset:4096
	ds_read_b64 v[146:147], v160 offset:4096
	ds_read_b64 v[148:149], v161 offset:4096
	ds_read_b64 v[138:139], v156 offset:4096
	ds_read_b64 v[140:141], v157 offset:4096
	ds_read_b64 v[134:135], v154 offset:4096
	ds_read_b64 v[136:137], v155 offset:4096
	v_max3_f32 v2, v52, v53, v54
	v_max3_f32 v2, v2, v55, v56
	v_max3_f32 v2, v2, v57, v58
	v_max3_f32 v2, v2, v59, v60
	v_max3_f32 v2, v2, v61, v62
	v_max3_f32 v2, v2, v63, v64
	v_max3_f32 v2, v2, v65, v66
	v_max_f32_e32 v2, v2, v67
	v_max3_f32 v170, v36, v37, v38
	v_max3_f32 v170, v170, v39, v40
	v_max3_f32 v170, v170, v41, v42
	v_max3_f32 v170, v170, v43, v44
	v_max3_f32 v170, v170, v45, v46
	v_max3_f32 v170, v170, v47, v48
	v_max3_f32 v170, v170, v49, v50
	v_max3_f32 v2, v2, v170, v51
	s_mov_b32 s3, 0x3e38aa3b
	v_mul_f32_e32 v2, s3, v2
	v_mov_b32_e32 v167, v2
	s_nop 1
	v_permlane32_swap_b32 v2, v167
	s_nop 1
	v_max3_f32 v166, v94, v2, v167
	v_sub_f32_e32 v168, v94, v166
	v_exp_f32_e32 v168, v168
	v_cmp_neq_f32_e32 vcc, v166, v94
	s_cbranch_vccz .Lat64_keep
	v_pk_mul_f32 v[34:35], v[34:35], v[168:169] op_sel_hi:[1,0]
	v_pk_mul_f32 v[32:33], v[32:33], v[168:169] op_sel_hi:[1,0]
	v_pk_mul_f32 v[30:31], v[30:31], v[168:169] op_sel_hi:[1,0]
	v_pk_mul_f32 v[28:29], v[28:29], v[168:169] op_sel_hi:[1,0]
	v_pk_mul_f32 v[26:27], v[26:27], v[168:169] op_sel_hi:[1,0]
	v_pk_mul_f32 v[24:25], v[24:25], v[168:169] op_sel_hi:[1,0]
	v_pk_mul_f32 v[22:23], v[22:23], v[168:169] op_sel_hi:[1,0]
	v_pk_mul_f32 v[20:21], v[20:21], v[168:169] op_sel_hi:[1,0]
	v_pk_mul_f32 v[18:19], v[18:19], v[168:169] op_sel_hi:[1,0]
	v_pk_mul_f32 v[16:17], v[16:17], v[168:169] op_sel_hi:[1,0]
	v_pk_mul_f32 v[14:15], v[14:15], v[168:169] op_sel_hi:[1,0]
	v_pk_mul_f32 v[12:13], v[12:13], v[168:169] op_sel_hi:[1,0]
	v_pk_mul_f32 v[10:11], v[10:11], v[168:169] op_sel_hi:[1,0]
	v_pk_mul_f32 v[8:9], v[8:9], v[168:169] op_sel_hi:[1,0]
	v_pk_mul_f32 v[6:7], v[6:7], v[168:169] op_sel_hi:[1,0]
	v_pk_mul_f32 v[4:5], v[4:5], v[168:169] op_sel_hi:[1,0]
.Lat64_keep:
	v_fma_f32 v52, v52, s3, -v166
	v_fma_f32 v53, v53, s3, -v166
	v_fma_f32 v54, v54, s3, -v166
	v_fma_f32 v55, v55, s3, -v166
	v_fma_f32 v56, v56, s3, -v166
	v_fma_f32 v57, v57, s3, -v166
	v_fma_f32 v58, v58, s3, -v166
	v_fma_f32 v59, v59, s3, -v166
	v_exp_f32_e32 v52, v52
	v_exp_f32_e32 v53, v53
	v_exp_f32_e32 v54, v54
	v_exp_f32_e32 v55, v55
	v_exp_f32_e32 v56, v56
	v_exp_f32_e32 v57, v57
	v_exp_f32_e32 v58, v58
	v_exp_f32_e32 v59, v59
	v_cvt_pk_bf16_f32 v150, v52, v53
	v_cvt_pk_bf16_f32 v151, v54, v55
	v_cvt_pk_bf16_f32 v152, v56, v57
	v_cvt_pk_bf16_f32 v153, v58, v59
	v_add_f32_e32 v52, v52, v53
	v_add_f32_e32 v54, v54, v55
	v_add_f32_e32 v56, v56, v57
	v_add_f32_e32 v58, v58, v59
	v_add_f32_e32 v52, v52, v54
	v_add_f32_e32 v56, v56, v58
	v_add_f32_e32 v52, v52, v56
	v_fma_f32 v60, v60, s3, -v166
	v_fma_f32 v61, v61, s3, -v166
	v_fma_f32 v62, v62, s3, -v166
	v_fma_f32 v63, v63, s3, -v166
	v_fma_f32 v64, v64, s3, -v166
	v_fma_f32 v65, v65, s3, -v166
	v_fma_f32 v66, v66, s3, -v166
	v_fma_f32 v67, v67, s3, -v166
	v_exp_f32_e32 v60, v60
	v_exp_f32_e32 v61, v61
	v_exp_f32_e32 v62, v62
	v_exp_f32_e32 v63, v63
	v_exp_f32_e32 v64, v64
	v_exp_f32_e32 v65, v65
	v_exp_f32_e32 v66, v66
	v_exp_f32_e32 v67, v67
	v_cvt_pk_bf16_f32 v154, v60, v61
	v_cvt_pk_bf16_f32 v155, v62, v63
	v_cvt_pk_bf16_f32 v156, v64, v65
	v_cvt_pk_bf16_f32 v157, v66, v67
	v_add_f32_e32 v60, v60, v61
	v_add_f32_e32 v62, v62, v63
	v_add_f32_e32 v64, v64, v65
	v_add_f32_e32 v66, v66, v67
	v_add_f32_e32 v60, v60, v62
	v_add_f32_e32 v64, v64, v66
	v_add_f32_e32 v60, v60, v64
	s_waitcnt lgkmcnt(0)
	v_mfma_f32_32x32x16_bf16 v[20:35], v[118:121], v[150:153], v[20:35]
	v_fma_f32 v36, v36, s3, -v166
	v_fma_f32 v37, v37, s3, -v166
	v_fma_f32 v38, v38, s3, -v166
	v_fma_f32 v39, v39, s3, -v166
	v_fma_f32 v40, v40, s3, -v166
	v_fma_f32 v41, v41, s3, -v166
	v_fma_f32 v42, v42, s3, -v166
	v_fma_f32 v43, v43, s3, -v166
	v_mfma_f32_32x32x16_bf16 v[4:19], v[134:137], v[150:153], v[4:19]
	v_exp_f32_e32 v36, v36
	v_exp_f32_e32 v37, v37
	v_exp_f32_e32 v38, v38
	v_exp_f32_e32 v39, v39
	v_exp_f32_e32 v40, v40
	v_exp_f32_e32 v41, v41
	v_exp_f32_e32 v42, v42
	v_exp_f32_e32 v43, v43
	v_mfma_f32_32x32x16_bf16 v[20:35], v[122:125], v[154:157], v[20:35]
	v_cvt_pk_bf16_f32 v158, v36, v37
	v_cvt_pk_bf16_f32 v159, v38, v39
	v_cvt_pk_bf16_f32 v160, v40, v41
	v_cvt_pk_bf16_f32 v161, v42, v43
	v_add_f32_e32 v36, v36, v37
	v_add_f32_e32 v38, v38, v39
	v_add_f32_e32 v40, v40, v41
	v_add_f32_e32 v42, v42, v43
	v_add_f32_e32 v36, v36, v38
	v_add_f32_e32 v40, v40, v42
	v_add_f32_e32 v36, v36, v40
	v_mfma_f32_32x32x16_bf16 v[4:19], v[138:141], v[154:157], v[4:19]
	v_fma_f32 v44, v44, s3, -v166
	v_fma_f32 v45, v45, s3, -v166
	v_fma_f32 v46, v46, s3, -v166
	v_fma_f32 v47, v47, s3, -v166
	v_fma_f32 v48, v48, s3, -v166
	v_fma_f32 v49, v49, s3, -v166
	v_fma_f32 v50, v50, s3, -v166
	v_fma_f32 v51, v51, s3, -v166
	v_exp_f32_e32 v44, v44
	v_exp_f32_e32 v45, v45
	v_exp_f32_e32 v46, v46
	v_exp_f32_e32 v47, v47
	v_exp_f32_e32 v48, v48
	v_exp_f32_e32 v49, v49
	v_exp_f32_e32 v50, v50
	v_exp_f32_e32 v51, v51
	v_cvt_pk_bf16_f32 v162, v44, v45
	v_cvt_pk_bf16_f32 v163, v46, v47
	v_cvt_pk_bf16_f32 v164, v48, v49
	v_cvt_pk_bf16_f32 v165, v50, v51
	v_add_f32_e32 v44, v44, v45
	v_add_f32_e32 v46, v46, v47
	v_add_f32_e32 v48, v48, v49
	v_add_f32_e32 v50, v50, v51
	v_add_f32_e32 v44, v44, v46
	v_add_f32_e32 v48, v48, v50
	v_add_f32_e32 v44, v44, v48
	v_add_f32_e32 v52, v52, v60
	v_add_f32_e32 v36, v36, v44
	v_add_f32_e32 v52, v52, v36
	v_fma_f32 v116, v116, v168, v52
	v_mfma_f32_32x32x16_bf16 v[20:35], v[126:129], v[158:161], v[20:35]
	v_mfma_f32_32x32x16_bf16 v[4:19], v[142:145], v[158:161], v[4:19]
	v_mfma_f32_32x32x16_bf16 v[20:35], v[130:133], v[162:165], v[20:35]
	v_mfma_f32_32x32x16_bf16 v[4:19], v[146:149], v[162:165], v[4:19]
	v_mov_b32_e32 v94, v166
	s_branch .LBB0_404
